# stack2: stack1 + phase-1 shift-row GEMV loads issued per 8 sub-steps + context attention units moved to workgroups 32..63
# speedup vs baseline: 1.0163x; 1.0003x over previous
; DI unsigned pk2(float a, float b) { f32x2 v = {a, b}; bf2_t r = __builtin_convertvector(v, bf2_t); return __builtin_bit_cast(unsigned, r); }
; DI void phase1(const Params& p) {
;     ...
;         for (int gi = gw; gi < DEPTH * G_L; gi += nw) {
;             const int l = gi / G_L, r = gi % G_L;
;             const bool which = r >= G_IN;
;             const int n0 = (which ? r - G_IN : r) * 16;
;             const int N = which ? FF : IN_DIM;
;             const bf16_t* W = (which ? p.wt_ff1 + (size_t)l * FF * DM : p.wt_in + (size_t)l * IN_DIM * DM) + (size_t)(n0 + fr) * DM + fq * 8;
;             float* dst = which ? p.shw_ff1 + (size_t)l * 5 * FF : p.shw_in + (size_t)l * 5 * IN_DIM;
;             const int c = fr < 5 ? fr : fr - 5;
;             const float* sh = p.mod + ((size_t)l * 5 + (c < 5 ? c : 0)) * 6144 + (which ? 3 : 0) * DM + fq * 8;
;             f32x4 acc = {0.f, 0.f, 0.f, 0.f};
; #pragma unroll 8
;             for (int ks = 0; ks < 32; ++ks) {
;                 const bf16x8 wv = *(const bf16x8*)(W + ks * 32);
;                 const f32x4 s0 = *(const f32x4*)(sh + ks * 32), s1 = *(const f32x4*)(sh + ks * 32 + 4);
;                 float sv[8] = {s0[0], s0[1], s0[2], s0[3], s1[0], s1[1], s1[2], s1[3]};
;                 u32x4 aw;
; #pragma unroll
;                 for (int j = 0; j < 4; ++j) {
;                     float a0 = sv[2 * j], a1 = sv[2 * j + 1];
;                     const unsigned hi = pk2(a0, a1);
;                     if (fr >= 5) { a0 -= __uint_as_float(hi << 16); a1 -= __uint_as_float(hi & 0xffff0000u); }
;                     aw[j] = fr < 5 ? hi : (fr < 10 ? pk2(a0, a1) : 0u);
;                 }
;                 acc = __builtin_amdgcn_mfma_f32_16x16x32_bf16(__builtin_bit_cast(bf16x8, aw), wv, acc, 0, 0, 0);
;             }
.LBB0_28:
	s_or_b64 exec, exec, s[44:45]
	v_mfma_f32_16x16x32_bf16 v[0:3], v[12:15], v[80:83], v[0:3]
	s_add_u32 s8, s8, 0x400
	s_addc_u32 s9, s9, 0
	s_cmpk_eq_i32 s8, 0x1000
	v_lshl_add_u64 v[34:35], v[34:35], 0, s[2:3]
	s_cbranch_scc1 .LBB0_93
.LBB0_29:
	v_lshl_add_u64 v[36:37], v[32:33], 0, s[8:9]
	global_load_dwordx4 v[136:139], v[36:37], off offset:16
	global_load_dwordx4 v[84:87], v[36:37], off
	global_load_dwordx4 v[52:55], v[34:35], off offset:-256
	global_load_dwordx4 v[140:143], v[36:37], off offset:144
	global_load_dwordx4 v[88:91], v[36:37], off offset:128
	global_load_dwordx4 v[56:59], v[34:35], off offset:-192
	global_load_dwordx4 v[144:147], v[36:37], off offset:272
	global_load_dwordx4 v[92:95], v[36:37], off offset:256
	global_load_dwordx4 v[60:63], v[34:35], off offset:-128
	global_load_dwordx4 v[148:151], v[36:37], off offset:400
	global_load_dwordx4 v[96:99], v[36:37], off offset:384
	global_load_dwordx4 v[64:67], v[34:35], off offset:-64
	global_load_dwordx4 v[152:155], v[36:37], off offset:528
	global_load_dwordx4 v[100:103], v[36:37], off offset:512
	global_load_dwordx4 v[68:71], v[34:35], off offset:0
	global_load_dwordx4 v[156:159], v[36:37], off offset:656
	global_load_dwordx4 v[104:107], v[36:37], off offset:640
	global_load_dwordx4 v[72:75], v[34:35], off offset:64
	global_load_dwordx4 v[160:163], v[36:37], off offset:784
	global_load_dwordx4 v[108:111], v[36:37], off offset:768
	global_load_dwordx4 v[76:79], v[34:35], off offset:128
	global_load_dwordx4 v[164:167], v[36:37], off offset:912
	global_load_dwordx4 v[112:115], v[36:37], off offset:896
	global_load_dwordx4 v[80:83], v[34:35], off offset:192
	s_waitcnt vmcnt(0)
	v_mov_b32_e32 v8, v136
	v_mov_b32_e32 v9, v137
	v_mov_b32_e32 v10, v138
	v_mov_b32_e32 v11, v139
	v_mov_b32_e32 v14, v84
	v_mov_b32_e32 v15, v85
	v_mov_b32_e32 v16, v86
	v_mov_b32_e32 v17, v87
	s_nop 0
	v_cvt_pk_bf16_f32 v12, v14, v15
	s_and_saveexec_b64 s[44:45], s[40:41]
	s_cbranch_execnz .LBB0_68
	s_or_b64 exec, exec, s[44:45]
	v_cvt_pk_bf16_f32 v13, v16, v17
	s_and_saveexec_b64 s[44:45], s[40:41]
	s_cbranch_execnz .LBB0_69

; DI unsigned pk2(float a, float b) { f32x2 v = {a, b}; bf2_t r = __builtin_convertvector(v, bf2_t); return __builtin_bit_cast(unsigned, r); }
; DI void phase1(const Params& p) {
;     ...
;                 const bf16x8 wv = *(const bf16x8*)(W + ks * 32);
;                 const f32x4 s0 = *(const f32x4*)(sh + ks * 32), s1 = *(const f32x4*)(sh + ks * 32 + 4);
;                 float sv[8] = {s0[0], s0[1], s0[2], s0[3], s1[0], s1[1], s1[2], s1[3]};
;                 u32x4 aw;
; #pragma unroll
;                 for (int j = 0; j < 4; ++j) {
;                     float a0 = sv[2 * j], a1 = sv[2 * j + 1];
;                     const unsigned hi = pk2(a0, a1);
;                     if (fr >= 5) { a0 -= __uint_as_float(hi << 16); a1 -= __uint_as_float(hi & 0xffff0000u); }
;                     aw[j] = fr < 5 ? hi : (fr < 10 ? pk2(a0, a1) : 0u);
;                 }
;                 acc = __builtin_amdgcn_mfma_f32_16x16x32_bf16(__builtin_bit_cast(bf16x8, aw), wv, acc, 0, 0, 0);
.LBB0_34:
	s_or_b64 exec, exec, s[44:45]
	s_nop 0
	v_mfma_f32_16x16x32_bf16 v[0:3], v[12:15], v[52:55], v[0:3]
	v_mov_b32_e32 v8, v140
	v_mov_b32_e32 v9, v141
	v_mov_b32_e32 v10, v142
	v_mov_b32_e32 v11, v143
	v_mov_b32_e32 v14, v88
	v_mov_b32_e32 v15, v89
	v_mov_b32_e32 v16, v90
	v_mov_b32_e32 v17, v91
	s_nop 0
	v_cvt_pk_bf16_f32 v12, v14, v15
	s_and_saveexec_b64 s[44:45], s[40:41]
	s_cbranch_execnz .LBB0_71
	s_or_b64 exec, exec, s[44:45]
	v_cvt_pk_bf16_f32 v13, v16, v17
	s_and_saveexec_b64 s[44:45], s[40:41]
	s_cbranch_execnz .LBB0_72

; DI unsigned pk2(float a, float b) { f32x2 v = {a, b}; bf2_t r = __builtin_convertvector(v, bf2_t); return __builtin_bit_cast(unsigned, r); }
; DI void phase1(const Params& p) {
;     ...
;                 const bf16x8 wv = *(const bf16x8*)(W + ks * 32);
;                 const f32x4 s0 = *(const f32x4*)(sh + ks * 32), s1 = *(const f32x4*)(sh + ks * 32 + 4);
;                 float sv[8] = {s0[0], s0[1], s0[2], s0[3], s1[0], s1[1], s1[2], s1[3]};
;                 u32x4 aw;
; #pragma unroll
;                 for (int j = 0; j < 4; ++j) {
;                     float a0 = sv[2 * j], a1 = sv[2 * j + 1];
;                     const unsigned hi = pk2(a0, a1);
;                     if (fr >= 5) { a0 -= __uint_as_float(hi << 16); a1 -= __uint_as_float(hi & 0xffff0000u); }
;                     aw[j] = fr < 5 ? hi : (fr < 10 ? pk2(a0, a1) : 0u);
;                 }
;                 acc = __builtin_amdgcn_mfma_f32_16x16x32_bf16(__builtin_bit_cast(bf16x8, aw), wv, acc, 0, 0, 0);
.LBB0_39:
	s_or_b64 exec, exec, s[44:45]
	s_nop 0
	v_mfma_f32_16x16x32_bf16 v[0:3], v[12:15], v[56:59], v[0:3]
	v_mov_b32_e32 v8, v144
	v_mov_b32_e32 v9, v145
	v_mov_b32_e32 v10, v146
	v_mov_b32_e32 v11, v147
	v_mov_b32_e32 v14, v92
	v_mov_b32_e32 v15, v93
	v_mov_b32_e32 v16, v94
	v_mov_b32_e32 v17, v95
	s_nop 0
	v_cvt_pk_bf16_f32 v12, v14, v15
	s_and_saveexec_b64 s[44:45], s[40:41]
	s_cbranch_execnz .LBB0_74
	s_or_b64 exec, exec, s[44:45]
	v_cvt_pk_bf16_f32 v13, v16, v17
	s_and_saveexec_b64 s[44:45], s[40:41]
	s_cbranch_execnz .LBB0_75

; DI unsigned pk2(float a, float b) { f32x2 v = {a, b}; bf2_t r = __builtin_convertvector(v, bf2_t); return __builtin_bit_cast(unsigned, r); }
; DI void phase1(const Params& p) {
;     ...
;                 const bf16x8 wv = *(const bf16x8*)(W + ks * 32);
;                 const f32x4 s0 = *(const f32x4*)(sh + ks * 32), s1 = *(const f32x4*)(sh + ks * 32 + 4);
;                 float sv[8] = {s0[0], s0[1], s0[2], s0[3], s1[0], s1[1], s1[2], s1[3]};
;                 u32x4 aw;
; #pragma unroll
;                 for (int j = 0; j < 4; ++j) {
;                     float a0 = sv[2 * j], a1 = sv[2 * j + 1];
;                     const unsigned hi = pk2(a0, a1);
;                     if (fr >= 5) { a0 -= __uint_as_float(hi << 16); a1 -= __uint_as_float(hi & 0xffff0000u); }
;                     aw[j] = fr < 5 ? hi : (fr < 10 ? pk2(a0, a1) : 0u);
;                 }
;                 acc = __builtin_amdgcn_mfma_f32_16x16x32_bf16(__builtin_bit_cast(bf16x8, aw), wv, acc, 0, 0, 0);
.LBB0_44:
	s_or_b64 exec, exec, s[44:45]
	s_nop 0
	v_mfma_f32_16x16x32_bf16 v[0:3], v[12:15], v[60:63], v[0:3]
	v_mov_b32_e32 v8, v148
	v_mov_b32_e32 v9, v149
	v_mov_b32_e32 v10, v150
	v_mov_b32_e32 v11, v151
	v_mov_b32_e32 v14, v96
	v_mov_b32_e32 v15, v97
	v_mov_b32_e32 v16, v98
	v_mov_b32_e32 v17, v99
	s_nop 0
	v_cvt_pk_bf16_f32 v12, v14, v15
	s_and_saveexec_b64 s[44:45], s[40:41]
	s_cbranch_execnz .LBB0_77
	s_or_b64 exec, exec, s[44:45]
	v_cvt_pk_bf16_f32 v13, v16, v17
	s_and_saveexec_b64 s[44:45], s[40:41]
	s_cbranch_execnz .LBB0_78

; DI unsigned pk2(float a, float b) { f32x2 v = {a, b}; bf2_t r = __builtin_convertvector(v, bf2_t); return __builtin_bit_cast(unsigned, r); }
; DI void phase1(const Params& p) {
;     ...
;                 const bf16x8 wv = *(const bf16x8*)(W + ks * 32);
;                 const f32x4 s0 = *(const f32x4*)(sh + ks * 32), s1 = *(const f32x4*)(sh + ks * 32 + 4);
;                 float sv[8] = {s0[0], s0[1], s0[2], s0[3], s1[0], s1[1], s1[2], s1[3]};
;                 u32x4 aw;
; #pragma unroll
;                 for (int j = 0; j < 4; ++j) {
;                     float a0 = sv[2 * j], a1 = sv[2 * j + 1];
;                     const unsigned hi = pk2(a0, a1);
;                     if (fr >= 5) { a0 -= __uint_as_float(hi << 16); a1 -= __uint_as_float(hi & 0xffff0000u); }
;                     aw[j] = fr < 5 ? hi : (fr < 10 ? pk2(a0, a1) : 0u);
;                 }
;                 acc = __builtin_amdgcn_mfma_f32_16x16x32_bf16(__builtin_bit_cast(bf16x8, aw), wv, acc, 0, 0, 0);
.LBB0_49:
	s_or_b64 exec, exec, s[44:45]
	s_nop 0
	v_mfma_f32_16x16x32_bf16 v[0:3], v[12:15], v[64:67], v[0:3]
	v_mov_b32_e32 v8, v152
	v_mov_b32_e32 v9, v153
	v_mov_b32_e32 v10, v154
	v_mov_b32_e32 v11, v155
	v_mov_b32_e32 v14, v100
	v_mov_b32_e32 v15, v101
	v_mov_b32_e32 v16, v102
	v_mov_b32_e32 v17, v103
	s_nop 0
	v_cvt_pk_bf16_f32 v12, v14, v15
	s_and_saveexec_b64 s[44:45], s[40:41]
	s_cbranch_execnz .LBB0_80
	s_or_b64 exec, exec, s[44:45]
	v_cvt_pk_bf16_f32 v13, v16, v17
	s_and_saveexec_b64 s[44:45], s[40:41]
	s_cbranch_execnz .LBB0_81

; DI unsigned pk2(float a, float b) { f32x2 v = {a, b}; bf2_t r = __builtin_convertvector(v, bf2_t); return __builtin_bit_cast(unsigned, r); }
; DI void phase1(const Params& p) {
;     ...
;                 const bf16x8 wv = *(const bf16x8*)(W + ks * 32);
;                 const f32x4 s0 = *(const f32x4*)(sh + ks * 32), s1 = *(const f32x4*)(sh + ks * 32 + 4);
;                 float sv[8] = {s0[0], s0[1], s0[2], s0[3], s1[0], s1[1], s1[2], s1[3]};
;                 u32x4 aw;
; #pragma unroll
;                 for (int j = 0; j < 4; ++j) {
;                     float a0 = sv[2 * j], a1 = sv[2 * j + 1];
;                     const unsigned hi = pk2(a0, a1);
;                     if (fr >= 5) { a0 -= __uint_as_float(hi << 16); a1 -= __uint_as_float(hi & 0xffff0000u); }
;                     aw[j] = fr < 5 ? hi : (fr < 10 ? pk2(a0, a1) : 0u);
;                 }
;                 acc = __builtin_amdgcn_mfma_f32_16x16x32_bf16(__builtin_bit_cast(bf16x8, aw), wv, acc, 0, 0, 0);
.LBB0_54:
	s_or_b64 exec, exec, s[44:45]
	s_nop 0
	v_mfma_f32_16x16x32_bf16 v[0:3], v[12:15], v[68:71], v[0:3]
	v_mov_b32_e32 v8, v156
	v_mov_b32_e32 v9, v157
	v_mov_b32_e32 v10, v158
	v_mov_b32_e32 v11, v159
	v_mov_b32_e32 v14, v104
	v_mov_b32_e32 v15, v105
	v_mov_b32_e32 v16, v106
	v_mov_b32_e32 v17, v107
	s_nop 0
	v_cvt_pk_bf16_f32 v12, v14, v15
	s_and_saveexec_b64 s[44:45], s[40:41]
	s_cbranch_execnz .LBB0_83
	s_or_b64 exec, exec, s[44:45]
	v_cvt_pk_bf16_f32 v13, v16, v17
	s_and_saveexec_b64 s[44:45], s[40:41]
	s_cbranch_execnz .LBB0_84

; DI unsigned pk2(float a, float b) { f32x2 v = {a, b}; bf2_t r = __builtin_convertvector(v, bf2_t); return __builtin_bit_cast(unsigned, r); }
; DI void phase1(const Params& p) {
;     ...
;                 const bf16x8 wv = *(const bf16x8*)(W + ks * 32);
;                 const f32x4 s0 = *(const f32x4*)(sh + ks * 32), s1 = *(const f32x4*)(sh + ks * 32 + 4);
;                 float sv[8] = {s0[0], s0[1], s0[2], s0[3], s1[0], s1[1], s1[2], s1[3]};
;                 u32x4 aw;
; #pragma unroll
;                 for (int j = 0; j < 4; ++j) {
;                     float a0 = sv[2 * j], a1 = sv[2 * j + 1];
;                     const unsigned hi = pk2(a0, a1);
;                     if (fr >= 5) { a0 -= __uint_as_float(hi << 16); a1 -= __uint_as_float(hi & 0xffff0000u); }
;                     aw[j] = fr < 5 ? hi : (fr < 10 ? pk2(a0, a1) : 0u);
;                 }
;                 acc = __builtin_amdgcn_mfma_f32_16x16x32_bf16(__builtin_bit_cast(bf16x8, aw), wv, acc, 0, 0, 0);
.LBB0_59:
	s_or_b64 exec, exec, s[44:45]
	s_nop 0
	v_mfma_f32_16x16x32_bf16 v[0:3], v[12:15], v[72:75], v[0:3]
	v_mov_b32_e32 v8, v160
	v_mov_b32_e32 v9, v161
	v_mov_b32_e32 v10, v162
	v_mov_b32_e32 v11, v163
	v_mov_b32_e32 v14, v108
	v_mov_b32_e32 v15, v109
	v_mov_b32_e32 v16, v110
	v_mov_b32_e32 v17, v111
	s_nop 0
	v_cvt_pk_bf16_f32 v12, v14, v15
	s_and_saveexec_b64 s[44:45], s[40:41]
	s_cbranch_execnz .LBB0_86
	s_or_b64 exec, exec, s[44:45]
	v_cvt_pk_bf16_f32 v13, v16, v17
	s_and_saveexec_b64 s[44:45], s[40:41]
	s_cbranch_execnz .LBB0_87

; DI unsigned pk2(float a, float b) { f32x2 v = {a, b}; bf2_t r = __builtin_convertvector(v, bf2_t); return __builtin_bit_cast(unsigned, r); }
; DI void phase1(const Params& p) {
;     ...
;                 const bf16x8 wv = *(const bf16x8*)(W + ks * 32);
;                 const f32x4 s0 = *(const f32x4*)(sh + ks * 32), s1 = *(const f32x4*)(sh + ks * 32 + 4);
;                 float sv[8] = {s0[0], s0[1], s0[2], s0[3], s1[0], s1[1], s1[2], s1[3]};
;                 u32x4 aw;
; #pragma unroll
;                 for (int j = 0; j < 4; ++j) {
;                     float a0 = sv[2 * j], a1 = sv[2 * j + 1];
;                     const unsigned hi = pk2(a0, a1);
;                     if (fr >= 5) { a0 -= __uint_as_float(hi << 16); a1 -= __uint_as_float(hi & 0xffff0000u); }
;                     aw[j] = fr < 5 ? hi : (fr < 10 ? pk2(a0, a1) : 0u);
;                 }
;                 acc = __builtin_amdgcn_mfma_f32_16x16x32_bf16(__builtin_bit_cast(bf16x8, aw), wv, acc, 0, 0, 0);
.LBB0_64:
	s_or_b64 exec, exec, s[44:45]
	s_nop 0
	v_mfma_f32_16x16x32_bf16 v[0:3], v[12:15], v[76:79], v[0:3]
	v_mov_b32_e32 v8, v164
	v_mov_b32_e32 v9, v165
	v_mov_b32_e32 v10, v166
	v_mov_b32_e32 v11, v167
	v_mov_b32_e32 v14, v112
	v_mov_b32_e32 v15, v113
	v_mov_b32_e32 v16, v114
	v_mov_b32_e32 v17, v115
	s_nop 0
	v_cvt_pk_bf16_f32 v12, v14, v15
	s_and_saveexec_b64 s[44:45], s[40:41]
	s_cbranch_execnz .LBB0_89
	s_or_b64 exec, exec, s[44:45]
	v_cvt_pk_bf16_f32 v13, v16, v17
	s_and_saveexec_b64 s[44:45], s[40:41]
	s_cbranch_execnz .LBB0_90

; DI void mixer_phase(const Params& p, int l, ldsp_t smem) {
;     ...
;     for (int u = blockIdx.x; u < 512; u += gridDim.x) attn_unit(p, l, (u & 7) >> 1, u & 1, u >> 3, false, smem);
;     if (!last)
;         for (int u = blockIdx.x; u < 32; u += gridDim.x) attn_unit(p, l, (u & 7) >> 1, u & 1, u >> 3, true, smem);
;     const int nT = last ? 128 : 136;
;     for (int u = blockIdx.x; u < nT * 4; u += gridDim.x) gmlp_unit(p, l, u >> 2, u & 3, smem);
.LBB0_166:
	v_readlane_b32 s4, v253, 0
	v_readlane_b32 s6, v255, 5
	v_readlane_b32 s7, v255, 6
	s_nop 3
	s_sub_u32 s4, s4, 32
	s_cmp_lt_u32 s4, 32
	s_cselect_b64 s[4:5], 0, -1
	s_or_b64 s[4:5], s[6:7], s[4:5]
	s_and_b64 s[6:7], s[6:7], exec
	s_movk_i32 s6, 0x220
	s_cselect_b32 s6, 0x200, s6
	s_and_b64 vcc, exec, s[4:5]
	s_cbranch_vccnz .LBB0_172
	s_ashr_i32 s49, s48, 31
	s_lshl_b64 s[4:5], s[48:49], 2
	s_add_u32 s4, s72, s4
	s_addc_u32 s5, s73, s5
	v_readlane_b32 s9, v253, 0
	s_nop 3
	s_sub_i32 s9, s9, 32
